# up-GEMM phase prologue: all six units' table loads issued together, one wait per wave instead of six serial load-wait-write rounds
# speedup vs baseline: 1.0115x; 1.0115x over previous
.LBB0_614:
	v_readlane_b32 s8, v251, 16
	s_mul_i32 s4, s52, 0x5800
	v_readlane_b32 s14, v251, 22
	s_mul_hi_u32 s3, s52, 0x5800
	v_readlane_b32 s15, v251, 23
	s_add_u32 s26, s14, s4
	v_readlane_b32 s10, v251, 18
	v_readlane_b32 s16, v251, 24
	s_addc_u32 s27, s15, s3
	s_mul_i32 s6, s52, 0x10800
	v_readlane_b32 s11, v251, 19
	v_readlane_b32 s17, v251, 25
	s_mul_hi_u32 s5, s52, 0x10800
	s_add_u32 s10, s16, s6
	v_readlane_b32 s18, v251, 26
	s_addc_u32 s11, s17, s5
	v_readlane_b32 s9, v251, 17
	v_readlane_b32 s19, v251, 27
	s_add_u32 s8, s18, s4
	s_mul_i32 s0, s52, 0x1600
	s_addc_u32 s9, s19, s3
	s_lshl_b64 s[4:5], s[0:1], 2
	v_readlane_b32 s3, v253, 22
	s_add_u32 s28, s3, s4
	v_readlane_b32 s3, v253, 23
	s_waitcnt lgkmcnt(0)
	s_barrier
	v_mbcnt_lo_u32_b32 v0, -1, 0
	v_mbcnt_hi_u32_b32 v0, -1, v0
	s_addc_u32 s29, s3, s5
	v_add_u32_e32 v1, s95, v0
	s_movk_i32 s3, 0xff
	v_readlane_b32 s12, v251, 20
	v_readlane_b32 s13, v251, 21
	v_cmp_lt_i32_e64 s[6:7], s3, v1
	v_add_u32_e32 v4, 0xfffffeff, v1
	v_cmp_gt_u32_e32 vcc, s58, v1
	v_readlane_b32 s20, v251, 28
	v_readlane_b32 s21, v251, 29
	v_readlane_b32 s22, v251, 30
	v_readlane_b32 s23, v251, 31
	v_readlane_b32 s4, v254, 43
	v_readlane_b32 s5, v254, 44
	v_ashrrev_i32_e32 v3, 7, v1
	s_movk_i32 s3, 0xb00
	v_and_b32_e32 v2, 0x7f, v1
	v_mul_lo_u32 v0, v3, s3
	v_or_b32_e32 v5, v0, v2
	v_cndmask_b32_e64 v0, 1.0, 4.0, vcc
	v_lshlrev_b32_e32 v3, 11, v3
	s_and_b64 s[4:5], exec, s[4:5]
	s_and_saveexec_b64 s[12:13], s[6:7]
	s_xor_b64 s[12:13], exec, s[12:13]
	s_cbranch_execz .Lmy_p5_b
	v_readlane_b32 s3, v254, 49
	s_nop 1
	v_add_u32_e32 v6, s3, v4
	v_med3_i32 v6, v6, 0, v222
	v_lshlrev_b32_e32 v6, 2, v6
	global_load_dword v6, v6, s[54:55]
	v_readlane_b32 s3, v254, 50
	s_nop 1
	v_add_u32_e32 v7, s3, v4
	v_med3_i32 v7, v7, 0, v222
	v_lshlrev_b32_e32 v7, 2, v7
	global_load_dword v7, v7, s[54:55]
	v_readlane_b32 s3, v254, 51
	s_nop 1
	v_add_u32_e32 v8, s3, v4
	v_med3_i32 v8, v8, 0, v222
	v_lshlrev_b32_e32 v8, 2, v8
	global_load_dword v8, v8, s[54:55]
	v_readlane_b32 s3, v254, 52
	s_nop 1
	v_add_u32_e32 v9, s3, v4
	v_med3_i32 v9, v9, 0, v222
	v_lshlrev_b32_e32 v9, 2, v9
	global_load_dword v9, v9, s[54:55]
	v_readlane_b32 s3, v254, 53
	s_nop 1
	v_add_u32_e32 v10, s3, v4
	v_med3_i32 v10, v10, 0, v222
	v_lshlrev_b32_e32 v10, 2, v10
	global_load_dword v10, v10, s[54:55]
	s_cmp_eq_u64 s[4:5], 0
	s_cbranch_scc1 .Lmy_p5_a5
	v_readlane_b32 s3, v254, 54
	s_nop 1
	v_add_u32_e32 v11, s3, v4
	v_med3_i32 v11, v11, 0, v222
	v_lshlrev_b32_e32 v11, 2, v11
	global_load_dword v11, v11, s[54:55]
.Lmy_p5_a5:
	s_add_i32 s3, 0, 0x20340
	v_lshl_add_u32 v12, v1, 2, s3
	v_readlane_b32 s3, v255, 2
	s_nop 1
	v_lshl_add_u32 v13, v1, 2, s3
	v_readlane_b32 s3, v255, 3
	s_nop 1
	v_lshl_add_u32 v14, v1, 2, s3
	v_readlane_b32 s3, v255, 4
	s_nop 1
	v_lshl_add_u32 v15, v1, 2, s3
	v_readlane_b32 s3, v255, 5
	s_nop 1
	v_lshl_add_u32 v16, v1, 2, s3
	v_readlane_b32 s3, v255, 6
	s_nop 1
	v_lshl_add_u32 v17, v1, 2, s3
	s_waitcnt vmcnt(0)
	ds_write_b32 v12, v6 offset:3072
	ds_write_b32 v13, v7 offset:3072
	ds_write_b32 v14, v8 offset:3072
	ds_write_b32 v15, v9 offset:3072
	ds_write_b32 v16, v10 offset:3072
	s_cmp_eq_u64 s[4:5], 0
	s_cbranch_scc1 .Lmy_p5_b
	ds_write_b32 v17, v11 offset:3072
.Lmy_p5_b:
	s_or_saveexec_b64 s[12:13], s[12:13]
	s_xor_b64 exec, exec, s[12:13]
	s_cbranch_execz .Lmy_p5_j
	v_readlane_b32 s3, v253, 55
	s_nop 1
	v_add_u32_e32 v6, s3, v5
	v_ashrrev_i32_e32 v7, 31, v6
	v_lshlrev_b64 v[6:7], 2, v[6:7]
	v_lshl_add_u64 v[8:9], s[28:29], 0, v[6:7]
	global_load_dword v16, v[8:9], off
	v_lshl_add_u64 v[8:9], s[26:27], 0, v[6:7]
	global_load_dword v17, v[8:9], off
	v_lshl_add_u64 v[8:9], s[10:11], 0, v[6:7]
	v_add_co_u32_e32 v10, vcc, 0x5000, v8
	global_load_dword v18, v[8:9], off
	s_nop 0
	v_addc_co_u32_e32 v11, vcc, 0, v9, vcc
	global_load_dword v19, v[10:11], off offset:2048
	v_add_co_u32_e32 v8, vcc, 0xb000, v8
	v_lshl_add_u64 v[6:7], s[8:9], 0, v[6:7]
	s_nop 0
	v_addc_co_u32_e32 v9, vcc, 0, v9, vcc
	global_load_dword v20, v[8:9], off
	global_load_dword v21, v[6:7], off
	v_readlane_b32 s3, v253, 56
	s_nop 1
	v_add_u32_e32 v6, s3, v5
	v_ashrrev_i32_e32 v7, 31, v6
	v_lshlrev_b64 v[6:7], 2, v[6:7]
	v_lshl_add_u64 v[8:9], s[28:29], 0, v[6:7]
	global_load_dword v22, v[8:9], off
	v_lshl_add_u64 v[8:9], s[26:27], 0, v[6:7]
	global_load_dword v23, v[8:9], off
	v_lshl_add_u64 v[8:9], s[10:11], 0, v[6:7]
	v_add_co_u32_e32 v10, vcc, 0x5000, v8
	global_load_dword v24, v[8:9], off
	s_nop 0
	v_addc_co_u32_e32 v11, vcc, 0, v9, vcc
	global_load_dword v25, v[10:11], off offset:2048
	v_add_co_u32_e32 v8, vcc, 0xb000, v8
	v_lshl_add_u64 v[6:7], s[8:9], 0, v[6:7]
	s_nop 0
	v_addc_co_u32_e32 v9, vcc, 0, v9, vcc
	global_load_dword v26, v[8:9], off
	global_load_dword v27, v[6:7], off
	v_readlane_b32 s3, v253, 57
	s_nop 1
	v_add_u32_e32 v6, s3, v5
	v_ashrrev_i32_e32 v7, 31, v6
	v_lshlrev_b64 v[6:7], 2, v[6:7]
	v_lshl_add_u64 v[8:9], s[28:29], 0, v[6:7]
	global_load_dword v28, v[8:9], off
	v_lshl_add_u64 v[8:9], s[26:27], 0, v[6:7]
	global_load_dword v29, v[8:9], off
	v_lshl_add_u64 v[8:9], s[10:11], 0, v[6:7]
	v_add_co_u32_e32 v10, vcc, 0x5000, v8
	global_load_dword v30, v[8:9], off
	s_nop 0
	v_addc_co_u32_e32 v11, vcc, 0, v9, vcc
	global_load_dword v31, v[10:11], off offset:2048
	v_add_co_u32_e32 v8, vcc, 0xb000, v8
	v_lshl_add_u64 v[6:7], s[8:9], 0, v[6:7]
	s_nop 0
	v_addc_co_u32_e32 v9, vcc, 0, v9, vcc
	global_load_dword v32, v[8:9], off
	global_load_dword v33, v[6:7], off
	v_readlane_b32 s3, v253, 58
	s_nop 1
	v_add_u32_e32 v6, s3, v5
	v_ashrrev_i32_e32 v7, 31, v6
	v_lshlrev_b64 v[6:7], 2, v[6:7]
	v_lshl_add_u64 v[8:9], s[28:29], 0, v[6:7]
	global_load_dword v34, v[8:9], off
	v_lshl_add_u64 v[8:9], s[26:27], 0, v[6:7]
	global_load_dword v35, v[8:9], off
	v_lshl_add_u64 v[8:9], s[10:11], 0, v[6:7]
	v_add_co_u32_e32 v10, vcc, 0x5000, v8
	global_load_dword v36, v[8:9], off
	s_nop 0
	v_addc_co_u32_e32 v11, vcc, 0, v9, vcc
	global_load_dword v37, v[10:11], off offset:2048
	v_add_co_u32_e32 v8, vcc, 0xb000, v8
	v_lshl_add_u64 v[6:7], s[8:9], 0, v[6:7]
	s_nop 0
	v_addc_co_u32_e32 v9, vcc, 0, v9, vcc
	global_load_dword v38, v[8:9], off
	global_load_dword v39, v[6:7], off
	v_readlane_b32 s3, v254, 19
	s_nop 1
	v_add_u32_e32 v6, s3, v5
	v_ashrrev_i32_e32 v7, 31, v6
	v_lshlrev_b64 v[6:7], 2, v[6:7]
	v_lshl_add_u64 v[8:9], s[28:29], 0, v[6:7]
	global_load_dword v40, v[8:9], off
	v_lshl_add_u64 v[8:9], s[26:27], 0, v[6:7]
	global_load_dword v41, v[8:9], off
	v_lshl_add_u64 v[8:9], s[10:11], 0, v[6:7]
	v_add_co_u32_e32 v10, vcc, 0x5000, v8
	global_load_dword v42, v[8:9], off
	s_nop 0
	v_addc_co_u32_e32 v11, vcc, 0, v9, vcc
	global_load_dword v43, v[10:11], off offset:2048
	v_add_co_u32_e32 v8, vcc, 0xb000, v8
	v_lshl_add_u64 v[6:7], s[8:9], 0, v[6:7]
	s_nop 0
	v_addc_co_u32_e32 v9, vcc, 0, v9, vcc
	global_load_dword v44, v[8:9], off
	global_load_dword v45, v[6:7], off
	s_cmp_eq_u64 s[4:5], 0
	s_cbranch_scc1 .Lmy_p5_b5
	v_readlane_b32 s3, v254, 23
	s_nop 1
	v_add_u32_e32 v6, s3, v5
	v_ashrrev_i32_e32 v7, 31, v6
	v_lshlrev_b64 v[6:7], 2, v[6:7]
	v_lshl_add_u64 v[8:9], s[28:29], 0, v[6:7]
	global_load_dword v46, v[8:9], off
	v_lshl_add_u64 v[8:9], s[26:27], 0, v[6:7]
	global_load_dword v47, v[8:9], off
	v_lshl_add_u64 v[8:9], s[10:11], 0, v[6:7]
	v_add_co_u32_e32 v10, vcc, 0x5000, v8
	global_load_dword v48, v[8:9], off
	s_nop 0
	v_addc_co_u32_e32 v11, vcc, 0, v9, vcc
	global_load_dword v49, v[10:11], off offset:2048
	v_add_co_u32_e32 v8, vcc, 0xb000, v8
	v_lshl_add_u64 v[6:7], s[8:9], 0, v[6:7]
	s_nop 0
	v_addc_co_u32_e32 v9, vcc, 0, v9, vcc
	global_load_dword v50, v[8:9], off
	global_load_dword v51, v[6:7], off
.Lmy_p5_b5:
	v_lshlrev_b32_e32 v52, 2, v2
	s_add_i32 s3, 0, 0x20340
	v_add3_u32 v53, s3, v3, v52
	v_readlane_b32 s3, v255, 2
	s_nop 1
	v_add3_u32 v54, s3, v3, v52
	v_readlane_b32 s3, v255, 3
	s_nop 1
	v_add3_u32 v55, s3, v3, v52
	v_readlane_b32 s3, v255, 4
	s_nop 1
	v_add3_u32 v56, s3, v3, v52
	v_readlane_b32 s3, v255, 5
	s_nop 1
	v_add3_u32 v57, s3, v3, v52
	v_readlane_b32 s3, v255, 6
	s_nop 1
	v_add3_u32 v58, s3, v3, v52
	s_waitcnt vmcnt(0)
	v_max_f32_e32 v16, v16, v16
	v_max_f32_e32 v16, 0xda24260, v16
	v_mul_f32_e32 v16, 0x3c010204, v16
	v_mul_f32_e32 v9, v16, v18
	v_mul_f32_e32 v9, v0, v9
	v_mul_f32_e32 v15, v16, v19
	v_add_f32_e32 v7, v18, v19
	v_mul_f32_e32 v15, v0, v15
	ds_write2st64_b32 v53, v9, v15 offset1:2
	v_add_f32_e32 v7, v7, v20
	v_mul_f32_e32 v9, v16, v20
	v_fmac_f32_e32 v21, v17, v7
	v_mul_f32_e32 v9, v0, v9
	v_mul_f32_e32 v21, v0, v21
	ds_write2st64_b32 v53, v9, v21 offset0:4 offset1:6
	v_max_f32_e32 v22, v22, v22
	v_max_f32_e32 v22, 0xda24260, v22
	v_mul_f32_e32 v22, 0x3c010204, v22
	v_mul_f32_e32 v9, v22, v24
	v_mul_f32_e32 v9, v0, v9
	v_mul_f32_e32 v15, v22, v25
	v_add_f32_e32 v7, v24, v25
	v_mul_f32_e32 v15, v0, v15
	ds_write2st64_b32 v54, v9, v15 offset1:2
	v_add_f32_e32 v7, v7, v26
	v_mul_f32_e32 v9, v22, v26
	v_fmac_f32_e32 v27, v23, v7
	v_mul_f32_e32 v9, v0, v9
	v_mul_f32_e32 v27, v0, v27
	ds_write2st64_b32 v54, v9, v27 offset0:4 offset1:6
	v_max_f32_e32 v28, v28, v28
	v_max_f32_e32 v28, 0xda24260, v28
	v_mul_f32_e32 v28, 0x3c010204, v28
	v_mul_f32_e32 v9, v28, v30
	v_mul_f32_e32 v9, v0, v9
	v_mul_f32_e32 v15, v28, v31
	v_add_f32_e32 v7, v30, v31
	v_mul_f32_e32 v15, v0, v15
	ds_write2st64_b32 v55, v9, v15 offset1:2
	v_add_f32_e32 v7, v7, v32
	v_mul_f32_e32 v9, v28, v32
	v_fmac_f32_e32 v33, v29, v7
	v_mul_f32_e32 v9, v0, v9
	v_mul_f32_e32 v33, v0, v33
	ds_write2st64_b32 v55, v9, v33 offset0:4 offset1:6
	v_max_f32_e32 v34, v34, v34
	v_max_f32_e32 v34, 0xda24260, v34
	v_mul_f32_e32 v34, 0x3c010204, v34
	v_mul_f32_e32 v9, v34, v36
	v_mul_f32_e32 v9, v0, v9
	v_mul_f32_e32 v15, v34, v37
	v_add_f32_e32 v7, v36, v37
	v_mul_f32_e32 v15, v0, v15
	ds_write2st64_b32 v56, v9, v15 offset1:2
	v_add_f32_e32 v7, v7, v38
	v_mul_f32_e32 v9, v34, v38
	v_fmac_f32_e32 v39, v35, v7
	v_mul_f32_e32 v9, v0, v9
	v_mul_f32_e32 v39, v0, v39
	ds_write2st64_b32 v56, v9, v39 offset0:4 offset1:6
	v_max_f32_e32 v40, v40, v40
	v_max_f32_e32 v40, 0xda24260, v40
	v_mul_f32_e32 v40, 0x3c010204, v40
	v_mul_f32_e32 v9, v40, v42
	v_mul_f32_e32 v9, v0, v9
	v_mul_f32_e32 v15, v40, v43
	v_add_f32_e32 v7, v42, v43
	v_mul_f32_e32 v15, v0, v15
	ds_write2st64_b32 v57, v9, v15 offset1:2
	v_add_f32_e32 v7, v7, v44
	v_mul_f32_e32 v9, v40, v44
	v_fmac_f32_e32 v45, v41, v7
	v_mul_f32_e32 v9, v0, v9
	v_mul_f32_e32 v45, v0, v45
	ds_write2st64_b32 v57, v9, v45 offset0:4 offset1:6
	s_cmp_eq_u64 s[4:5], 0
	s_cbranch_scc1 .Lmy_p5_j
	v_max_f32_e32 v46, v46, v46
	v_max_f32_e32 v46, 0xda24260, v46
	v_mul_f32_e32 v46, 0x3c010204, v46
	v_mul_f32_e32 v9, v46, v48
	v_mul_f32_e32 v9, v0, v9
	v_mul_f32_e32 v15, v46, v49
	v_add_f32_e32 v7, v48, v49
	v_mul_f32_e32 v15, v0, v15
	ds_write2st64_b32 v58, v9, v15 offset1:2
	v_add_f32_e32 v7, v7, v50
	v_mul_f32_e32 v9, v46, v50
	v_fmac_f32_e32 v51, v47, v7
	v_mul_f32_e32 v9, v0, v9
	v_mul_f32_e32 v51, v0, v51
	ds_write2st64_b32 v58, v9, v51 offset0:4 offset1:6
.Lmy_p5_j:
	s_or_b64 exec, exec, s[12:13]
.LBB0_632:
	s_waitcnt lgkmcnt(0)
	s_barrier
	v_mbcnt_lo_u32_b32 v0, -1, 0
	v_mbcnt_hi_u32_b32 v0, -1, v0
	s_movk_i32 s4, 0x7e
	v_add_u32_e32 v0, s95, v0
	s_mul_hi_u32 s78, s52, 0x580000
	v_bfe_i32 v3, v0, 27, 1
	v_lshlrev_b32_e32 v1, 4, v0
	v_lshrrev_b32_e32 v3, 22, v3
	v_add_u32_e32 v3, v1, v3
	v_and_b32_e32 v3, 0xfffffc00, v3
	v_sub_u32_e32 v3, v1, v3
	v_ashrrev_i32_e32 v2, 31, v0
	v_lshrrev_b32_e32 v4, 4, v3
	v_lshrrev_b32_e32 v2, 26, v2
	v_bitop3_b32 v3, v4, v3, 32 bitop3:0x6c
	v_add_u32_e32 v2, v0, v2
	v_ashrrev_i32_e32 v5, 31, v3
	v_ashrrev_i32_e32 v2, 6, v2
	v_lshrrev_b32_e32 v5, 26, v5
	v_lshlrev_b32_e32 v4, 3, v2
	v_add_u32_e32 v5, v3, v5
	v_and_b32_e32 v4, -16, v4
	v_ashrrev_i32_e32 v6, 6, v5
	v_and_b32_e32 v5, 0xc0, v5
	v_add_u32_e32 v4, v6, v4
	v_sub_u32_e32 v3, v3, v5
	v_lshlrev_b32_e32 v2, 5, v2
	v_ashrrev_i16_sdwa v3, v214, sext(v3) dst_sel:DWORD dst_unused:UNUSED_PAD src0_sel:DWORD src1_sel:BYTE_0
	v_lshrrev_b32_e32 v5, 6, v4
	v_lshlrev_b32_e32 v6, 3, v4
	v_and_b32_e32 v2, 32, v2
	v_bfe_i32 v3, v3, 0, 16
	v_mul_lo_u32 v5, v5, s4
	v_and_b32_e32 v6, 0x78, v6
	v_bfe_u32 v7, v4, 4, 2
	v_add3_u32 v5, v5, v6, v7
	v_add_lshl_u32 v2, v2, v3, 1
	v_add_u32_e32 v1, 0x2000, v1
	v_lshl_add_u32 v230, v5, 10, v2
	v_lshl_add_u32 v236, v4, 10, v2
	v_ashrrev_i32_e32 v2, 31, v1
	v_lshrrev_b32_e32 v2, 22, v2
	v_add_u32_e32 v2, v1, v2
	v_ashrrev_i32_e32 v2, 10, v2
	v_mul_i32_i24_e32 v3, 0x400, v2
	v_sub_u32_e32 v1, v1, v3
	v_lshrrev_b32_e32 v3, 4, v1
	v_bitop3_b32 v1, v3, v1, 32 bitop3:0x6c
	v_ashrrev_i32_e32 v4, 31, v1
	v_lshrrev_b32_e32 v4, 26, v4
	v_lshlrev_b32_e32 v3, 3, v2
	v_add_u32_e32 v4, v1, v4
	v_writelane_b32 v255, s52, 28
	s_mul_i32 s0, s52, 0x580000
	v_readlane_b32 s3, v254, 9
	v_and_b32_e32 v3, -16, v3
	v_ashrrev_i32_e32 v5, 6, v4
	s_add_u32 s62, s3, s0
	v_readlane_b32 s3, v254, 12
	v_add_u32_e32 v3, v5, v3
	v_and_b32_e32 v4, 0xc0, v4
	s_addc_u32 s63, s3, s78
	v_readfirstlane_b32 s3, v0
	v_sub_u32_e32 v1, v1, v4
	v_lshrrev_b32_e32 v4, 6, v3
	v_mul_lo_u32 v4, v4, s4
	s_ashr_i32 s4, s3, 6
	s_ashr_i32 s60, s3, 8
	s_lshl_b32 s64, s4, 10
	v_readlane_b32 s5, v253, 61
	s_add_u32 s12, s62, s5
	v_lshlrev_b32_e32 v2, 5, v2
	v_ashrrev_i16_sdwa v1, v214, sext(v1) dst_sel:DWORD dst_unused:UNUSED_PAD src0_sel:DWORD src1_sel:BYTE_0
	s_addc_u32 s13, s63, 0
	s_add_i32 s65, s64, 0
	v_and_b32_e32 v2, 32, v2
	v_bfe_i32 v1, v1, 0, 16
	s_add_i32 s66, s65, 0x10000
	s_add_i32 s67, s65, 0x12000
	v_add_lshl_u32 v1, v2, v1, 1
	s_mov_b32 m0, s66
	s_add_u32 s6, s12, 0x20000
	v_lshl_add_u32 v240, v3, 10, v1
	global_load_lds_dwordx4 v236, s[12:13]
	s_mov_b32 m0, s67
	s_addc_u32 s7, s13, 0
	s_add_i32 s68, s65, 0x14000
	global_load_lds_dwordx4 v240, s[12:13]
	s_mov_b32 m0, s68
	s_add_i32 s69, s65, 0x16000
	v_lshlrev_b32_e32 v5, 3, v3
	global_load_lds_dwordx4 v236, s[6:7]
	s_mov_b32 m0, s69
	v_and_b32_e32 v5, 0x78, v5
	v_bfe_u32 v6, v3, 4, 2
	global_load_lds_dwordx4 v240, s[6:7]
	v_readlane_b32 s6, v254, 0
	v_add3_u32 v4, v4, v5, v6
	s_mov_b32 m0, s65
	v_readlane_b32 s7, v254, 1
	s_add_i32 s70, s65, 0x2000
	v_lshl_add_u32 v238, v4, 10, v1
	s_add_i32 s71, s65, 0x4000
	s_add_i32 s72, s65, 0x6000
	v_writelane_b32 v255, s53, 29
	global_load_lds_dwordx4 v230, s[6:7]
	s_mov_b32 m0, s70
	s_cmp_eq_u32 s60, 1
	global_load_lds_dwordx4 v238, s[6:7]
	v_readlane_b32 s6, v254, 2
	s_mov_b32 m0, s71
	v_readlane_b32 s7, v254, 3
	v_writelane_b32 v255, s0, 36
	s_mov_b32 s31, s87
	s_movk_i32 s81, 0x4000
	v_mov_b32_e32 v229, 1
	s_movk_i32 s87, 0x7e
	global_load_lds_dwordx4 v230, s[6:7]
	s_mov_b32 m0, s72
	s_nop 0
	global_load_lds_dwordx4 v238, s[6:7]
	s_cselect_b64 s[6:7], -1, 0
	v_writelane_b32 v255, s6, 34
	s_cmp_lg_u32 s60, 1
	s_nop 0
	v_writelane_b32 v255, s7, 35
	s_cbranch_scc1 .LBB0_634
	s_barrier

.LBB0_732:
	v_mbcnt_lo_u32_b32 v32, -1, 0
	v_mbcnt_hi_u32_b32 v32, -1, v32
	s_and_b32 s8, s11, 0x3e0
	v_lshlrev_b32_e32 v0, 2, v32
	v_and_b32_e32 v2, 28, v0
	v_and_b32_e32 v0, -8, v32
	v_add_u32_e32 v0, s10, v0
	v_ashrrev_i32_e32 v1, 31, v0
	v_lshlrev_b64 v[0:1], 12, v[0:1]
	v_lshl_add_u64 v[0:1], s[6:7], 0, v[0:1]
	s_lshl_b32 s0, s8, 2
	v_lshl_add_u64 v[0:1], v[0:1], 0, s[0:1]
	v_lshlrev_b32_e32 v230, 2, v2
	v_lshl_add_u64 v[28:29], v[0:1], 0, v[230:231]
	v_add_co_u32_e32 v4, vcc, s54, v28
	global_load_dwordx4 v[0:3], v[28:29], off
	s_nop 0
	v_addc_co_u32_e32 v5, vcc, 0, v29, vcc
	v_add_co_u32_e32 v16, vcc, s55, v28
	global_load_dwordx4 v[8:11], v[4:5], off offset:-4096
	s_waitcnt lgkmcnt(0)
	global_load_dwordx4 v[4:7], v[4:5], off
	v_addc_co_u32_e32 v17, vcc, 0, v29, vcc
	v_add_co_u32_e32 v24, vcc, s56, v28
	global_load_dwordx4 v[12:15], v[16:17], off offset:-4096
	s_nop 0
	global_load_dwordx4 v[16:19], v[16:17], off
	v_addc_co_u32_e32 v25, vcc, 0, v29, vcc
	v_add_co_u32_e32 v28, vcc, s61, v28
	global_load_dwordx4 v[20:23], v[24:25], off offset:-4096
	s_nop 0
	global_load_dwordx4 v[24:27], v[24:25], off
	v_addc_co_u32_e32 v29, vcc, 0, v29, vcc
	global_load_dwordx4 v[28:31], v[28:29], off
	v_cmp_gt_i32_e32 vcc, 8, v32
	s_waitcnt vmcnt(0)
	v_max_f32_e64 v0, |v0|, |v0|
	v_max_f32_e64 v1, |v1|, |v1|
	v_max_f32_e64 v2, |v2|, |v2|
	v_max_f32_e64 v3, |v3|, |v3|
	v_max_f32_e64 v8, |v8|, |v8|
	v_max_f32_e32 v0, v0, v8
	v_max_f32_e64 v8, |v9|, |v9|
	v_max_f32_e32 v1, v1, v8
	v_max_f32_e64 v8, |v10|, |v10|
	v_max3_f32 v0, v0, |v4|, |v12|
	v_mbcnt_lo_u32_b32 v4, -1, 0
	v_mbcnt_hi_u32_b32 v4, -1, v4
	v_max3_f32 v1, v1, |v5|, |v13|
	v_lshlrev_b32_e32 v4, 2, v4
	v_xor_b32_e32 v4, 32, v4
	v_max3_f32 v0, v0, |v16|, |v20|
	v_max3_f32 v1, v1, |v17|, |v21|
	v_max_f32_e32 v2, v2, v8
	v_max3_f32 v2, v2, |v6|, |v14|
	v_max3_f32 v0, v0, |v24|, |v28|
	ds_bpermute_b32 v4, v4, v0
	v_max3_f32 v1, v1, |v25|, |v29|
	v_max3_f32 v2, v2, |v18|, |v22|
	v_max3_f32 v2, v2, |v26|, |v30|
	v_max_f32_e64 v8, |v11|, |v11|
	s_waitcnt lgkmcnt(0)
	v_max_f32_e32 v4, v4, v4
	v_max_f32_e32 v0, v0, v4
	v_mbcnt_lo_u32_b32 v4, -1, 0
	v_mbcnt_hi_u32_b32 v4, -1, v4
	v_max_f32_e32 v3, v3, v8
	v_lshlrev_b32_e32 v4, 2, v4
	v_xor_b32_e32 v4, 64, v4
	ds_bpermute_b32 v4, v4, v0
	v_max3_f32 v3, v3, |v7|, |v15|
	v_max3_f32 v3, v3, |v19|, |v23|
	v_max3_f32 v3, v3, |v27|, |v31|
	s_waitcnt lgkmcnt(0)
	v_max_f32_e32 v4, v4, v4
	v_max_f32_e32 v0, v0, v4
	v_mbcnt_lo_u32_b32 v4, -1, 0
	v_mbcnt_hi_u32_b32 v4, -1, v4
	v_mbcnt_lo_u32_b32 v5, -1, 0
	v_mbcnt_hi_u32_b32 v5, -1, v5
	s_nop 0
	v_lshlrev_b32_e32 v5, 2, v5
	v_xor_b32_e32 v5, 32, v5
	ds_bpermute_b32 v5, v5, v1
	v_lshlrev_b32_e32 v4, 2, v4
	v_xor_b32_e32 v4, 0x80, v4
	ds_bpermute_b32 v4, v4, v0
	s_waitcnt lgkmcnt(1)
	v_max_f32_e32 v5, v5, v5
	v_max_f32_e32 v1, v1, v5
	v_mbcnt_lo_u32_b32 v5, -1, 0
	v_mbcnt_hi_u32_b32 v5, -1, v5
	s_nop 0
	v_lshlrev_b32_e32 v5, 2, v5
	v_xor_b32_e32 v5, 64, v5
	ds_bpermute_b32 v5, v5, v1
	s_waitcnt lgkmcnt(0)
	v_max_f32_e32 v5, v5, v5
	v_max_f32_e32 v1, v1, v5
	v_mbcnt_lo_u32_b32 v5, -1, 0
	v_mbcnt_hi_u32_b32 v5, -1, v5
	v_mbcnt_lo_u32_b32 v6, -1, 0
	v_mbcnt_hi_u32_b32 v6, -1, v6
	s_nop 0
	v_lshlrev_b32_e32 v6, 2, v6
	v_xor_b32_e32 v6, 32, v6
	ds_bpermute_b32 v6, v6, v2
	v_lshlrev_b32_e32 v5, 2, v5
	v_xor_b32_e32 v5, 0x80, v5
	ds_bpermute_b32 v5, v5, v1
	s_waitcnt lgkmcnt(1)
	v_max_f32_e32 v6, v6, v6
	v_max_f32_e32 v2, v2, v6
	v_mbcnt_lo_u32_b32 v6, -1, 0
	v_mbcnt_hi_u32_b32 v6, -1, v6
	s_nop 0
	v_lshlrev_b32_e32 v6, 2, v6
	v_xor_b32_e32 v6, 64, v6
	ds_bpermute_b32 v6, v6, v2
	s_waitcnt lgkmcnt(0)
	v_max_f32_e32 v6, v6, v6
	v_max_f32_e32 v2, v2, v6
	v_mbcnt_lo_u32_b32 v6, -1, 0
	v_mbcnt_hi_u32_b32 v6, -1, v6
	v_mbcnt_lo_u32_b32 v7, -1, 0
	v_mbcnt_hi_u32_b32 v7, -1, v7
	s_nop 0
	v_lshlrev_b32_e32 v7, 2, v7
	v_xor_b32_e32 v7, 32, v7
	ds_bpermute_b32 v7, v7, v3
	v_lshlrev_b32_e32 v6, 2, v6
	v_xor_b32_e32 v6, 0x80, v6
	ds_bpermute_b32 v6, v6, v2
	s_waitcnt lgkmcnt(1)
	v_max_f32_e32 v7, v7, v7
	v_max_f32_e32 v3, v3, v7
	v_mbcnt_lo_u32_b32 v7, -1, 0
	v_mbcnt_hi_u32_b32 v7, -1, v7
	s_nop 0
	v_lshlrev_b32_e32 v7, 2, v7
	v_xor_b32_e32 v7, 64, v7
	ds_bpermute_b32 v7, v7, v3
	s_waitcnt lgkmcnt(0)
	v_max_f32_e32 v7, v7, v7
	v_max_f32_e32 v3, v3, v7
	v_mbcnt_lo_u32_b32 v7, -1, 0
	v_mbcnt_hi_u32_b32 v7, -1, v7
	s_nop 0
	v_lshlrev_b32_e32 v7, 2, v7
	v_xor_b32_e32 v7, 0x80, v7
	ds_bpermute_b32 v7, v7, v3
	s_and_saveexec_b64 s[8:9], vcc
	s_cbranch_execz .LBB0_731
	v_max_f32_e32 v4, v4, v4
	v_max_f32_e32 v0, v0, v0
	s_add_u32 s12, s3, s0
	s_waitcnt lgkmcnt(0)
	v_max_f32_e32 v7, v7, v7
	v_max_f32_e32 v3, v3, v3
	v_max_f32_e32 v6, v6, v6
	v_max_f32_e32 v2, v2, v2
	v_max_f32_e32 v5, v5, v5
	v_max_f32_e32 v1, v1, v1
	v_max_f32_e32 v0, v0, v4
	s_addc_u32 s13, s4, 0
	v_max_f32_e32 v3, v3, v7
	v_max_f32_e32 v2, v2, v6
	v_max_f32_e32 v1, v1, v5
	global_atomic_umax v230, v0, s[12:13]
	global_atomic_umax v230, v1, s[12:13] offset:4
	global_atomic_umax v230, v2, s[12:13] offset:8
	global_atomic_umax v230, v3, s[12:13] offset:12
	s_branch .LBB0_731
.LBB0_742:
	s_mov_b64 s[6:7], 0
